# speedup vs baseline: 1.0065x; 1.0065x over previous
;     ...
; #pragma unroll
;         for (int a = 0; a < 2; ++a)
; #pragma unroll
;             for (int b = 0; b < 2; ++b)
; #pragma unroll
;                 for (int m = 0; m < 4; ++m)
; #pragma unroll
;                     for (int n = 0; n < 2; ++n) acc[a][b][m][n] = (f32x4){0.f, 0.f, 0.f, 0.f};
;         cur = nxt; cA = nA; cB = nB; ++ui;
.LBB0_119:
	s_add_i32 s41, s40, -2
	s_add_u32 s42, s10, 0x100
	v_mov_b32_e32 v0, 0
	s_addc_u32 s43, s11, 0
	s_mov_b32 s2, 0
	v_mov_b64_e32 v[0:1], 0
	v_mov_b64_e32 v[2:3], 0
	v_mov_b64_e32 v[4:5], 0
	v_mov_b64_e32 v[6:7], 0
	v_mov_b64_e32 v[8:9], 0
	v_mov_b64_e32 v[10:11], 0
	v_mov_b64_e32 v[12:13], 0
	v_mov_b64_e32 v[14:15], 0
	v_mov_b64_e32 v[16:17], 0
	v_mov_b64_e32 v[18:19], 0
	v_mov_b64_e32 v[20:21], 0
	v_mov_b64_e32 v[22:23], 0
	v_mov_b64_e32 v[24:25], 0
	v_mov_b64_e32 v[26:27], 0
	v_mov_b64_e32 v[28:29], 0
	v_mov_b64_e32 v[30:31], 0
	v_mov_b64_e32 v[32:33], 0
	v_mov_b64_e32 v[34:35], 0
	v_mov_b64_e32 v[36:37], 0
	v_mov_b64_e32 v[38:39], 0
	v_mov_b64_e32 v[40:41], 0
	v_mov_b64_e32 v[42:43], 0
	v_mov_b64_e32 v[44:45], 0
	v_mov_b64_e32 v[46:47], 0
	v_mov_b64_e32 v[48:49], 0
	v_mov_b64_e32 v[50:51], 0
	v_mov_b64_e32 v[52:53], 0
	v_mov_b64_e32 v[54:55], 0
	v_mov_b64_e32 v[56:57], 0
	v_mov_b64_e32 v[58:59], 0
	v_mov_b64_e32 v[60:61], 0
	v_mov_b64_e32 v[62:63], 0
	v_mov_b64_e32 v[66:67], 0
	v_mov_b64_e32 v[68:69], 0
	v_mov_b64_e32 v[70:71], 0
	v_mov_b64_e32 v[72:73], 0
	v_mov_b64_e32 v[74:75], 0
	v_mov_b64_e32 v[76:77], 0
	v_mov_b64_e32 v[78:79], 0
	v_mov_b64_e32 v[80:81], 0
	v_mov_b64_e32 v[82:83], 0
	v_mov_b64_e32 v[84:85], 0
	v_mov_b64_e32 v[86:87], 0
	v_mov_b64_e32 v[88:89], 0
	v_mov_b64_e32 v[90:91], 0
	v_mov_b64_e32 v[92:93], 0
	v_mov_b64_e32 v[94:95], 0
	v_mov_b64_e32 v[96:97], 0
	v_mov_b64_e32 v[98:99], 0
	v_mov_b64_e32 v[100:101], 0
	v_mov_b64_e32 v[102:103], 0
	v_mov_b64_e32 v[104:105], 0
	v_mov_b64_e32 v[106:107], 0
	v_mov_b64_e32 v[108:109], 0
	v_mov_b64_e32 v[110:111], 0
	v_mov_b64_e32 v[112:113], 0
	v_mov_b64_e32 v[114:115], 0
	v_mov_b64_e32 v[116:117], 0
	v_mov_b64_e32 v[118:119], 0
	v_mov_b64_e32 v[120:121], 0
	v_mov_b64_e32 v[122:123], 0
	v_mov_b64_e32 v[124:125], 0
	v_mov_b64_e32 v[126:127], 0
	v_mov_b64_e32 v[128:129], 0

; #define PG8_STAGE(bufoff, gbase, voff) do { _Pragma("unroll") for (int _i = 0; _i < 2; ++_i) \
;         __builtin_amdgcn_global_load_lds((const unsigned*)((const char*)(gbase) + (voff)[_i]), (LAS unsigned*)(lds + (bufoff) + ldsw + _i * 8192), 16, 0, 0); } while (0)
; #define PG8_WAIT_V(n) asm volatile("s_waitcnt vmcnt(" #n ")" ::: "memory")
; #define PG8_BAR __builtin_amdgcn_s_barrier()
;     ...
;     for (int i = 0; i < 2; ++i) { int R, C; stage_rc(tid * 16 + i * 8192, R, C); const int Rb = Epi::PERM ? ((R & ~31) + perm32(R & 31)) : R;
;         voffA[i] = (unsigned)(R * LD + C) * 2u; voffB[i] = (unsigned)(Rb * LD + C) * 2u; }
;     const size_t kstep = (size_t)(BK * 2);
;     const size_t hstep = (size_t)HALF * LD * 2;
;     const size_t tstep = 2 * hstep;
;     const unsigned ldsw = (unsigned)wid * 1024u;
;     const int aoff = lds_byte(wr * 64 + fr, fq * 8), boff = lds_byte(wc * 32 + fr, fq * 8);
;     ...
;     Unit cur, nxt; int ui = 0;
;     if (!S.next(0, cur)) return;
;     f32x4 acc[2][2][4][2];
; #pragma unroll
;     for (int a = 0; a < 2; ++a)
; #pragma unroll
;         for (int b = 0; b < 2; ++b)
; #pragma unroll
;             for (int m = 0; m < 4; ++m)
; #pragma unroll
;                 for (int n = 0; n < 2; ++n) acc[a][b][m][n] = (f32x4){0.f, 0.f, 0.f, 0.f};
;     bf16x8 At[4][2], B0[2][2], B1[2][2];
;     const char* cA = (const char*)g.A + (size_t)cur.pm * tstep + (size_t)cur.k0 * kstep; const char* cB = (const char*)g.Bt + (size_t)cur.pn * tstep + (size_t)cur.k0 * kstep;
;     PG8_STAGE(PG8_SB(0, 0), cB, voffB); PG8_STAGE(PG8_SA(0, 0), cA, voffA); PG8_STAGE(PG8_SB(0, 1), cB + hstep, voffB); PG8_STAGE(PG8_SA(0, 1), cA + hstep, voffA);
;     if (wr == 1) PG8_BAR;
;     PG8_WAIT_V(4); PG8_BAR;
;     PG8_STAGE(PG8_SB(1, 0), cB + kstep, voffB); PG8_STAGE(PG8_SA(1, 0), cA + kstep, voffA); PG8_STAGE(PG8_SB(1, 1), cB + hstep + kstep, voffB);
;     PG8_WAIT_V(6); PG8_BAR;
.LBB0_145:
	v_lshrrev_b32_e32 v18, 1, v12
	v_and_b32_e32 v140, 24, v18
	s_lshl_b32 s3, s3, 5
	v_and_b32_e32 v17, 15, v12
	v_lshlrev_b32_e32 v18, 1, v140
	v_lshlrev_b32_e32 v12, 2, v12
	s_and_b32 s24, s3, 0x60
	s_add_i32 m0, s20, 0x18000
	v_lshl_add_u64 v[6:7], v[6:7], 0, s[16:17]
	v_lshl_or_b32 v141, s8, 6, v17
	v_lshl_or_b32 v17, v17, 6, v18
	s_lshl_b32 s8, s8, 13
	v_and_b32_e32 v12, 32, v12
	s_lshl_b32 s3, s24, 7
	s_waitcnt vmcnt(4)
	s_barrier
	global_load_lds_dwordx4 v[6:7], off
	v_lshl_add_u64 v[4:5], v[4:5], 0, s[16:17]
	s_add_i32 m0, s20, 0x1a000
	s_add_i32 s25, s20, 0x8000
	s_add_i32 s26, s20, 0xa000
	v_bitop3_b32 v18, v17, s8, v12 bitop3:0xde
	global_load_lds_dwordx4 v[4:5], off
	v_lshl_add_u64 v[2:3], v[2:3], 0, s[16:17]
	s_mov_b32 m0, s25
	s_add_u32 s8, s4, 0x84080
	global_load_lds_dwordx4 v[2:3], off
	v_lshl_add_u64 v[0:1], v[0:1], 0, s[16:17]
	s_mov_b32 m0, s26
	s_addc_u32 s9, s5, 0
	global_load_lds_dwordx4 v[0:1], off
	s_add_i32 m0, s20, 0x1c000
	v_lshl_add_u64 v[0:1], s[8:9], 0, v[64:65]
	global_load_lds_dwordx4 v[0:1], off
	v_lshl_add_u64 v[0:1], s[8:9], 0, v[130:131]
	s_add_i32 m0, s20, 0x1e000
	s_movk_i32 s10, 0x840
	global_load_lds_dwordx4 v[0:1], off
	v_lshrrev_b32_e32 v1, 1, v14
	v_mul_lo_u32 v0, v13, s10
	s_mov_b32 s9, 0x8400
	v_bitop3_b32 v142, v17, s3, v12 bitop3:0xde
	s_mul_i32 s8, s2, 0x108000
	v_mad_u64_u32 v[0:1], s[2:3], v1, s9, v[0:1]
	v_or_b32_e32 v0, v0, v15
	s_add_u32 s2, s46, s8
	v_add_lshl_u32 v0, v0, v16, 1
	v_mov_b32_e32 v1, v65
	s_addc_u32 s3, s47, 0
	v_lshl_add_u64 v[136:137], s[2:3], 0, v[0:1]
	v_lshrrev_b32_e32 v1, 1, v8
	v_mul_lo_u32 v0, v9, s10
	v_mad_u64_u32 v[0:1], s[8:9], v1, s9, v[0:1]
	v_or_b32_e32 v0, v0, v10
	s_waitcnt vmcnt(6)
	v_add_lshl_u32 v0, v0, v11, 1
	v_mov_b32_e32 v1, v65
	v_lshl_add_u64 v[138:139], s[2:3], 0, v[0:1]
	v_mov_b32_e32 v0, 0
	s_mov_b32 s27, -2
	s_mov_b64 s[8:9], 0x1aea4080
	v_add_u32_e32 v143, 0, v18
	v_mov_b64_e32 v[0:1], 0
	v_mov_b64_e32 v[2:3], 0
	v_mov_b64_e32 v[4:5], 0
	v_mov_b64_e32 v[6:7], 0
	v_mov_b64_e32 v[8:9], 0
	v_mov_b64_e32 v[10:11], 0
	v_mov_b64_e32 v[12:13], 0
	v_mov_b64_e32 v[14:15], 0
	v_mov_b64_e32 v[16:17], 0
	v_mov_b64_e32 v[18:19], 0
	v_mov_b64_e32 v[20:21], 0
	v_mov_b64_e32 v[22:23], 0
	v_mov_b64_e32 v[24:25], 0
	v_mov_b64_e32 v[26:27], 0
	v_mov_b64_e32 v[28:29], 0
	v_mov_b64_e32 v[30:31], 0
	v_mov_b64_e32 v[32:33], 0
	v_mov_b64_e32 v[34:35], 0
	v_mov_b64_e32 v[36:37], 0
	v_mov_b64_e32 v[38:39], 0
	v_mov_b64_e32 v[40:41], 0
	v_mov_b64_e32 v[42:43], 0
	v_mov_b64_e32 v[44:45], 0
	v_mov_b64_e32 v[46:47], 0
	v_mov_b64_e32 v[48:49], 0
	v_mov_b64_e32 v[50:51], 0
	v_mov_b64_e32 v[52:53], 0
	v_mov_b64_e32 v[54:55], 0
	v_mov_b64_e32 v[56:57], 0
	v_mov_b64_e32 v[58:59], 0
	v_mov_b64_e32 v[60:61], 0
	v_mov_b64_e32 v[62:63], 0
	v_mov_b64_e32 v[66:67], 0
	v_mov_b64_e32 v[68:69], 0
	v_mov_b64_e32 v[70:71], 0
	v_mov_b64_e32 v[72:73], 0
	v_mov_b64_e32 v[74:75], 0
	v_mov_b64_e32 v[76:77], 0
	v_mov_b64_e32 v[78:79], 0
	v_mov_b64_e32 v[80:81], 0
	v_mov_b64_e32 v[82:83], 0
	v_mov_b64_e32 v[84:85], 0
	v_mov_b64_e32 v[86:87], 0
	v_mov_b64_e32 v[88:89], 0
	v_mov_b64_e32 v[90:91], 0
	v_mov_b64_e32 v[92:93], 0
	v_mov_b64_e32 v[94:95], 0
	v_mov_b64_e32 v[96:97], 0
	v_mov_b64_e32 v[98:99], 0
	v_mov_b64_e32 v[100:101], 0
	v_mov_b64_e32 v[102:103], 0
	v_mov_b64_e32 v[104:105], 0
	v_mov_b64_e32 v[106:107], 0
	v_mov_b64_e32 v[108:109], 0
	v_mov_b64_e32 v[110:111], 0
	v_mov_b64_e32 v[112:113], 0
	v_mov_b64_e32 v[114:115], 0
	v_mov_b64_e32 v[116:117], 0
	v_mov_b64_e32 v[118:119], 0
	v_mov_b64_e32 v[120:121], 0
	v_mov_b64_e32 v[122:123], 0
	v_mov_b64_e32 v[124:125], 0
	v_mov_b64_e32 v[126:127], 0
	v_mov_b64_e32 v[128:129], 0
	s_barrier

;     ...
;         const bool has_next = S.next(ui + 1, nxt);
;         const char* nA = has_next ? (const char*)g.A + (size_t)nxt.pm * tstep + (size_t)nxt.k0 * kstep : cA; const char* nB = has_next ? (const char*)g.Bt + (size_t)nxt.pn * tstep + (size_t)nxt.k0 * kstep : cB;
;         const int nt = cur.nt;
;         for (int t = 0; t < nt; t += 2) {
;             const bool last = (t == nt - 2);
;             if (last && has_next && gate != nullptr && nxt.pm >= 32) {
;     ...
; #pragma unroll
;         for (int a = 0; a < 2; ++a)
; #pragma unroll
;             for (int b = 0; b < 2; ++b)
; #pragma unroll
;                 for (int m = 0; m < 4; ++m)
; #pragma unroll
;                     for (int n = 0; n < 2; ++n) acc[a][b][m][n] = (f32x4){0.f, 0.f, 0.f, 0.f};
;         cur = nxt; cA = nA; cB = nB; ++ui;
.LBB0_472:
	v_readlane_b32 s2, v252, 58
	s_add_u32 s47, s24, s82
	v_readlane_b32 s3, v252, 59
	s_addc_u32 s89, s25, 0
	s_add_i32 s1, s6, -2
	s_and_b64 s[10:11], s[2:3], s[10:11]
	v_mov_b32_e32 v8, 0
	s_cmp_gt_i32 s34, 31
	s_mov_b32 s12, 0
	s_cselect_b64 s[14:15], -1, 0
	v_mov_b64_e32 v[0:1], 0
	v_mov_b64_e32 v[2:3], 0
	v_mov_b64_e32 v[4:5], 0
	v_mov_b64_e32 v[6:7], 0
	v_mov_b64_e32 v[8:9], 0
	v_mov_b64_e32 v[10:11], 0
	v_mov_b64_e32 v[12:13], 0
	v_mov_b64_e32 v[14:15], 0
	v_mov_b64_e32 v[16:17], 0
	v_mov_b64_e32 v[18:19], 0
	v_mov_b64_e32 v[20:21], 0
	v_mov_b64_e32 v[22:23], 0
	v_mov_b64_e32 v[24:25], 0
	v_mov_b64_e32 v[26:27], 0
	v_mov_b64_e32 v[28:29], 0
	v_mov_b64_e32 v[30:31], 0
	v_mov_b64_e32 v[32:33], 0
	v_mov_b64_e32 v[34:35], 0
	v_mov_b64_e32 v[36:37], 0
	v_mov_b64_e32 v[38:39], 0
	v_mov_b64_e32 v[40:41], 0
	v_mov_b64_e32 v[42:43], 0
	v_mov_b64_e32 v[44:45], 0
	v_mov_b64_e32 v[46:47], 0
	v_mov_b64_e32 v[48:49], 0
	v_mov_b64_e32 v[50:51], 0
	v_mov_b64_e32 v[52:53], 0
	v_mov_b64_e32 v[54:55], 0
	v_mov_b64_e32 v[56:57], 0
	v_mov_b64_e32 v[58:59], 0
	v_mov_b64_e32 v[60:61], 0
	v_mov_b64_e32 v[62:63], 0
	v_mov_b64_e32 v[66:67], 0
	v_mov_b64_e32 v[68:69], 0
	v_mov_b64_e32 v[70:71], 0
	v_mov_b64_e32 v[72:73], 0
	v_mov_b64_e32 v[74:75], 0
	v_mov_b64_e32 v[76:77], 0
	v_mov_b64_e32 v[78:79], 0
	v_mov_b64_e32 v[80:81], 0
	v_mov_b64_e32 v[82:83], 0
	v_mov_b64_e32 v[84:85], 0
	v_mov_b64_e32 v[86:87], 0
	v_mov_b64_e32 v[88:89], 0
	v_mov_b64_e32 v[90:91], 0
	v_mov_b64_e32 v[92:93], 0
	v_mov_b64_e32 v[94:95], 0
	v_mov_b64_e32 v[96:97], 0
	v_mov_b64_e32 v[98:99], 0
	v_mov_b64_e32 v[100:101], 0
	v_mov_b64_e32 v[102:103], 0
	v_mov_b64_e32 v[104:105], 0
	v_mov_b64_e32 v[106:107], 0
	v_mov_b64_e32 v[108:109], 0
	v_mov_b64_e32 v[110:111], 0
	v_mov_b64_e32 v[112:113], 0
	v_mov_b64_e32 v[114:115], 0
	v_mov_b64_e32 v[116:117], 0
	v_mov_b64_e32 v[118:119], 0
	v_mov_b64_e32 v[120:121], 0
	v_mov_b64_e32 v[122:123], 0
	v_mov_b64_e32 v[124:125], 0
	v_mov_b64_e32 v[126:127], 0
	v_mov_b64_e32 v[128:129], 0
	s_branch .LBB0_476

; #define PG8_STAGE(bufoff, gbase, voff) do { _Pragma("unroll") for (int _i = 0; _i < 2; ++_i) \
;         __builtin_amdgcn_global_load_lds((const unsigned*)((const char*)(gbase) + (voff)[_i]), (LAS unsigned*)(lds + (bufoff) + ldsw + _i * 8192), 16, 0, 0); } while (0)
; #define PG8_WAIT_V(n) asm volatile("s_waitcnt vmcnt(" #n ")" ::: "memory")
; #define PG8_BAR __builtin_amdgcn_s_barrier()
;     ...
;     for (int i = 0; i < 2; ++i) { int R, C; stage_rc(tid * 16 + i * 8192, R, C); const int Rb = Epi::PERM ? ((R & ~31) + perm32(R & 31)) : R;
;         voffA[i] = (unsigned)(R * LD + C) * 2u; voffB[i] = (unsigned)(Rb * LD + C) * 2u; }
;     const size_t kstep = (size_t)(BK * 2);
;     const size_t hstep = (size_t)HALF * LD * 2;
;     const size_t tstep = 2 * hstep;
;     const unsigned ldsw = (unsigned)wid * 1024u;
;     const int aoff = lds_byte(wr * 64 + fr, fq * 8), boff = lds_byte(wc * 32 + fr, fq * 8);
;     ...
;     Unit cur, nxt; int ui = 0;
;     if (!S.next(0, cur)) return;
;     f32x4 acc[2][2][4][2];
; #pragma unroll
;     for (int a = 0; a < 2; ++a)
; #pragma unroll
;         for (int b = 0; b < 2; ++b)
; #pragma unroll
;             for (int m = 0; m < 4; ++m)
; #pragma unroll
;                 for (int n = 0; n < 2; ++n) acc[a][b][m][n] = (f32x4){0.f, 0.f, 0.f, 0.f};
;     bf16x8 At[4][2], B0[2][2], B1[2][2];
;     const char* cA = (const char*)g.A + (size_t)cur.pm * tstep + (size_t)cur.k0 * kstep; const char* cB = (const char*)g.Bt + (size_t)cur.pn * tstep + (size_t)cur.k0 * kstep;
;     PG8_STAGE(PG8_SB(0, 0), cB, voffB); PG8_STAGE(PG8_SA(0, 0), cA, voffA); PG8_STAGE(PG8_SB(0, 1), cB + hstep, voffB); PG8_STAGE(PG8_SA(0, 1), cA + hstep, voffA);
;     if (wr == 1) PG8_BAR;
;     PG8_WAIT_V(4); PG8_BAR;
;     PG8_STAGE(PG8_SB(1, 0), cB + kstep, voffB); PG8_STAGE(PG8_SA(1, 0), cA + kstep, voffA); PG8_STAGE(PG8_SB(1, 1), cB + hstep + kstep, voffB);
;     PG8_WAIT_V(6); PG8_BAR;
.LBB0_1274:
	v_bfe_u32 v136, v16, 4, 2
	v_and_b32_e32 v17, 15, v16
	v_lshlrev_b32_e32 v18, 4, v136
	v_lshlrev_b32_e32 v16, 2, v16
	s_and_b32 s12, s2, 3
	v_lshl_or_b32 v137, s6, 6, v17
	v_lshl_or_b32 v17, v17, 6, v18
	s_lshl_b32 s2, s6, 13
	v_and_b32_e32 v16, 32, v16
	s_add_i32 m0, s15, 0x18000
	v_lshl_add_u64 v[6:7], v[6:7], 0, s[16:17]
	v_bitop3_b32 v18, v17, s2, v16 bitop3:0xde
	s_lshl_b32 s2, s12, 12
	s_waitcnt vmcnt(4)
	s_barrier
	global_load_lds_dwordx4 v[6:7], off
	v_lshl_add_u64 v[4:5], v[4:5], 0, s[16:17]
	s_add_i32 m0, s15, 0x1a000
	s_add_i32 s21, s15, 0x8000
	s_add_i32 s22, s15, 0xa000
	global_load_lds_dwordx4 v[4:5], off
	v_lshl_add_u64 v[2:3], v[2:3], 0, s[16:17]
	s_mov_b32 m0, s21
	s_add_u32 s6, s0, 0x84080
	global_load_lds_dwordx4 v[2:3], off
	v_lshl_add_u64 v[0:1], v[0:1], 0, s[16:17]
	s_mov_b32 m0, s22
	s_addc_u32 s7, s1, 0
	global_load_lds_dwordx4 v[0:1], off
	s_add_i32 m0, s15, 0x1c000
	v_lshl_add_u64 v[0:1], s[6:7], 0, v[64:65]
	global_load_lds_dwordx4 v[0:1], off
	v_lshl_add_u64 v[0:1], s[6:7], 0, v[130:131]
	s_add_i32 m0, s15, 0x1e000
	s_movk_i32 s8, 0x840
	global_load_lds_dwordx4 v[0:1], off
	v_lshrrev_b32_e32 v1, 1, v8
	v_mul_lo_u32 v0, v10, s8
	s_mov_b32 s7, 0x8400
	v_bitop3_b32 v138, v17, s2, v16 bitop3:0xde
	s_mul_i32 s6, s3, 0x108000
	v_mad_u64_u32 v[0:1], s[2:3], v1, s7, v[0:1]
	v_or_b32_e32 v0, v0, v9
	s_add_u32 s2, s46, s6
	v_add_lshl_u32 v0, v0, v11, 1
	v_mov_b32_e32 v1, v65
	s_addc_u32 s3, s47, 0
	v_lshl_add_u64 v[132:133], s[2:3], 0, v[0:1]
	v_lshrrev_b32_e32 v1, 1, v12
	v_mul_lo_u32 v0, v14, s8
	v_mad_u64_u32 v[0:1], s[6:7], v1, s7, v[0:1]
	v_or_b32_e32 v0, v0, v13
	s_waitcnt vmcnt(6)
	v_add_lshl_u32 v0, v0, v15, 1
	v_mov_b32_e32 v1, v65
	v_lshl_add_u64 v[134:135], s[2:3], 0, v[0:1]
	v_mov_b32_e32 v0, 0
	s_mov_b32 s23, -2
	s_mov_b64 s[6:7], 0x18984080
	v_add_u32_e32 v139, 0, v18
	v_mov_b64_e32 v[0:1], 0
	v_mov_b64_e32 v[2:3], 0
	v_mov_b64_e32 v[4:5], 0
	v_mov_b64_e32 v[6:7], 0
	v_mov_b64_e32 v[8:9], 0
	v_mov_b64_e32 v[10:11], 0
	v_mov_b64_e32 v[12:13], 0
	v_mov_b64_e32 v[14:15], 0
	v_mov_b64_e32 v[16:17], 0
	v_mov_b64_e32 v[18:19], 0
	v_mov_b64_e32 v[20:21], 0
	v_mov_b64_e32 v[22:23], 0
	v_mov_b64_e32 v[24:25], 0
	v_mov_b64_e32 v[26:27], 0
	v_mov_b64_e32 v[28:29], 0
	v_mov_b64_e32 v[30:31], 0
	v_mov_b64_e32 v[32:33], 0
	v_mov_b64_e32 v[34:35], 0
	v_mov_b64_e32 v[36:37], 0
	v_mov_b64_e32 v[38:39], 0
	v_mov_b64_e32 v[40:41], 0
	v_mov_b64_e32 v[42:43], 0
	v_mov_b64_e32 v[44:45], 0
	v_mov_b64_e32 v[46:47], 0
	v_mov_b64_e32 v[48:49], 0
	v_mov_b64_e32 v[50:51], 0
	v_mov_b64_e32 v[52:53], 0
	v_mov_b64_e32 v[54:55], 0
	v_mov_b64_e32 v[56:57], 0
	v_mov_b64_e32 v[58:59], 0
	v_mov_b64_e32 v[60:61], 0
	v_mov_b64_e32 v[62:63], 0
	v_mov_b64_e32 v[66:67], 0
	v_mov_b64_e32 v[68:69], 0
	v_mov_b64_e32 v[70:71], 0
	v_mov_b64_e32 v[72:73], 0
	v_mov_b64_e32 v[74:75], 0
	v_mov_b64_e32 v[76:77], 0
	v_mov_b64_e32 v[78:79], 0
	v_mov_b64_e32 v[80:81], 0
	v_mov_b64_e32 v[82:83], 0
	v_mov_b64_e32 v[84:85], 0
	v_mov_b64_e32 v[86:87], 0
	v_mov_b64_e32 v[88:89], 0
	v_mov_b64_e32 v[90:91], 0
	v_mov_b64_e32 v[92:93], 0
	v_mov_b64_e32 v[94:95], 0
	v_mov_b64_e32 v[96:97], 0
	v_mov_b64_e32 v[98:99], 0
	v_mov_b64_e32 v[100:101], 0
	v_mov_b64_e32 v[102:103], 0
	v_mov_b64_e32 v[104:105], 0
	v_mov_b64_e32 v[106:107], 0
	v_mov_b64_e32 v[108:109], 0
	v_mov_b64_e32 v[110:111], 0
	v_mov_b64_e32 v[112:113], 0
	v_mov_b64_e32 v[114:115], 0
	v_mov_b64_e32 v[116:117], 0
	v_mov_b64_e32 v[118:119], 0
	v_mov_b64_e32 v[120:121], 0
	v_mov_b64_e32 v[122:123], 0
	v_mov_b64_e32 v[124:125], 0
	v_mov_b64_e32 v[126:127], 0
	v_mov_b64_e32 v[128:129], 0
	s_barrier
